# bundle + tail-first stagger in merge and out phases (run 1)
# baseline (speedup 1.0000x reference)
; #define GAS __attribute__((address_space(1)))
;     __device__ __forceinline__ GAS float* outp() const { return (GAS float*)rd(17); }
;     __device__ __forceinline__ GAS unsigned char* wsp() const { return (GAS unsigned char*)rd(18); }
;     ...
;     for (int i = 0; i < 2; ++i) { int R, C; stage_rc(tid * 16 + i * 8192, R, C); const int Rb = (R & ~31) + perm32(R & 31);
;         voffA[i] = (unsigned)(R * K + C) * 2u; voffB[i] = (unsigned)(Rb * K + C) * 2u; }
;     const size_t kstep = (size_t)(BK * 2);
;     const size_t hstep = (size_t)HALF * K * 2;
;     const size_t tstep = 2 * hstep;
;     const unsigned ldsw = (unsigned)wid * 1024u;
;     const int aoff = lds_byte(wr * 64 + fr, fq * 8), boff = lds_byte(wc * 32 + fr, fq * 8);
;     ...
;     Unit cur, nxt; int ui = 0;
;     if (!S.template next<MODE>(0, cur)) return;
;     Acc acc;
; #pragma unroll
;     for (int a = 0; a < 2; ++a)
; #pragma unroll
;         for (int b = 0; b < 2; ++b)
; #pragma unroll
;             for (int m = 0; m < 4; ++m)
; #pragma unroll
;                 for (int n = 0; n < 2; ++n) acc[a][b][m][n] = (f32x4){0.f, 0.f, 0.f, 0.f};
;     bf16x8 At[4][2], B0[2][2], B1[2][2];
;     const GAS char* cA = (const GAS char*)(g.A + (size_t)cur.seg * g.a_seg) + (size_t)cur.pm * tstep + (MODE ? (size_t)cur.k0 * kstep : 0); const GAS char* cB = (const GAS char*)(g.Bt + (size_t)cur.seg * g.b_seg) + (size_t)cur.pn * tstep + (MODE ? (size_t)cur.k0 * kstep : 0);
;     PG8_STAGE(PG8_SB(0, 0), cB, voffB); PG8_STAGE(PG8_SB(0, 1), cB + hstep, voffB); PG8_STAGE(PG8_SA(0, 0), cA, voffA); PG8_STAGE(PG8_SA(0, 1), cA + hstep, voffA);
;     if (wr == 1) PG8_BAR;
;     PG8_WAIT_V(2); PG8_BAR;
;     PG8_STAGE(PG8_SB(1, 0), cB + kstep, voffB); PG8_STAGE(PG8_SA(1, 0), cA + kstep, voffA); PG8_STAGE(PG8_SB(1, 1), cB + hstep + kstep, voffB);
;     PG8_WAIT_V(6); PG8_BAR;
; __global__ void __launch_bounds__(512, 2) mega_fwd(Params p) {
;     ...
;             pg8::Gemm g{(const GAS bf16*)(F.wsp() + WS_MERGED), (const GAS bf16*)(F.wsp() + WS_WOUT) + (size_t)l * D * D, 0, 0, MTOT / 256, D / 256, 1, D, 4, WGM_SQ};
;             pg8::Order S; S.init(g, F.G, (int)blockIdx.x);
;             pg8::EpiOut E{F.wsp(), F.outp(), l == DEPTH - 1 ? 1 : 0};
;             pg8::gemm_phase(F.lds, g, S, E, F.wave);
;             { __syncthreads(); pg8::EpiOutSlab E2{F.wsp()}; pg8::gemm_phase<pg8::EpiOutSlab, 1>(F.lds, g, S, E2, F.wave); }
.LBB0_1171:
.Lor_pre:
	v_readlane_b32 s8, v241, 46
	s_waitcnt lgkmcnt(0)
	s_barrier
	v_mov_b32_e32 v0, s8
	ds_read2_b64 v[0:3], v0 offset1:1
	v_readlane_b32 s14, v242, 58
	v_readlane_b32 s15, v242, 59
	s_andn2_b64 vcc, exec, s[14:15]
	s_waitcnt lgkmcnt(0)
	v_readfirstlane_b32 s9, v1
	v_cndmask_b32_e64 v1, 0, 1, s[14:15]
	v_readfirstlane_b32 s13, v3
	v_readfirstlane_b32 s12, v2
	v_readfirstlane_b32 s8, v0
	v_mov_b32_e32 v0, v173
	v_cmp_ne_u32_e64 s[58:59], 1, v1
	s_cbranch_vccnz .LBB0_1173
	v_readlane_b32 s14, v242, 62
	s_mov_b32 s60, s14
	v_readlane_b32 s14, v242, 63
	s_mov_b32 s52, s14
.LBB0_1173:
	s_add_u32 s20, s12, 0x2fc80000
	v_readlane_b32 s14, v240, 8
	s_addc_u32 s68, s13, 0
	s_lshl_b32 s14, s14, 21
	v_readlane_b32 s15, v240, 9
	s_add_u32 s14, s12, s14
	s_addc_u32 s15, s13, 0
	s_add_u32 s69, s14, 0x4200000
	s_addc_u32 s70, s15, 0
	v_readlane_b32 s14, v243, 60
	v_readlane_b32 s15, v243, 61
	s_and_b64 vcc, exec, s[58:59]
	s_nop 0
	v_cndmask_b32_e64 v1, 0, 1, s[14:15]
	v_cmp_ne_u32_e64 s[58:59], 1, v1
	s_cmp_lg_u32 s100, 0
	s_cbranch_scc1 .Lor_a
	s_bitcmp1_b32 s101, 0
	s_cbranch_scc0 .Lor_a
	s_mov_b32 s100, 1
	s_branch .LBB0_1274
.Lor_a:
	s_cbranch_vccnz .LBB0_1274
	v_mbcnt_lo_u32_b32 v0, -1, v0
	v_mbcnt_hi_u32_b32 v14, -1, v0
	v_lshl_add_u32 v0, v14, 4, s95
	v_ashrrev_i32_e32 v1, 31, v0
	v_lshrrev_b32_e32 v1, 22, v1
	v_add_u32_e32 v1, v0, v1
	v_ashrrev_i32_e32 v8, 10, v1
	v_mul_i32_i24_e32 v1, 0x400, v8
	v_sub_u32_e32 v1, v0, v1
	v_lshrrev_b32_e32 v2, 4, v1
	v_bitop3_b32 v1, v2, v1, 32 bitop3:0x6c
	v_ashrrev_i32_e32 v3, 31, v1
	v_lshrrev_b32_e32 v3, 26, v3
	v_add_u32_e32 v3, v1, v3
	v_lshlrev_b32_e32 v2, 3, v8
	v_ashrrev_i32_e32 v9, 6, v3
	v_and_b32_e32 v3, 0xc0, v3
	v_and_b32_e32 v2, -16, v2
	v_sub_u32_e32 v1, v1, v3
	v_add_u32_e32 v2, v9, v2
	v_ashrrev_i16_sdwa v1, v213, sext(v1) dst_sel:DWORD dst_unused:UNUSED_PAD src0_sel:DWORD src1_sel:BYTE_0
	v_lshlrev_b32_e32 v4, 5, v8
	v_bfe_i32 v10, v1, 0, 16
	v_lshlrev_b32_e32 v1, 1, v2
	v_lshrrev_b32_e32 v3, 2, v2
	v_and_b32_e32 v5, 3, v9
	s_mov_b32 s14, 0x1fffe0
	v_and_b32_e32 v4, 32, v4
	v_and_b32_e32 v1, 24, v1
	v_and_b32_e32 v3, 4, v3
	v_and_or_b32 v5, v2, s14, v5
	v_or3_b32 v1, v5, v3, v1
	v_add_lshl_u32 v3, v4, v10, 1
	v_add_u32_e32 v0, 0x2000, v0
	v_lshl_add_u32 v172, v1, 11, v3
	v_ashrrev_i32_e32 v1, 31, v0
	v_lshrrev_b32_e32 v1, 22, v1
	v_add_u32_e32 v1, v0, v1
	v_ashrrev_i32_e32 v11, 10, v1
	v_mul_i32_i24_e32 v1, 0x400, v11
	v_sub_u32_e32 v0, v0, v1
	v_lshrrev_b32_e32 v1, 4, v0
	v_bitop3_b32 v0, v1, v0, 32 bitop3:0x6c
	v_lshl_add_u32 v160, v2, 11, v3
	v_ashrrev_i32_e32 v2, 31, v0
	v_lshrrev_b32_e32 v2, 26, v2
	v_add_u32_e32 v2, v0, v2
	v_ashrrev_i32_e32 v12, 6, v2
	v_and_b32_e32 v2, 0xffc0, v2
	v_lshlrev_b32_e32 v1, 3, v11
	v_sub_u32_e32 v0, v0, v2
	v_and_b32_e32 v1, -16, v1
	v_lshrrev_b16_e32 v2, 7, v0
	v_add_u32_e32 v1, v12, v1
	v_and_b32_e32 v2, 1, v2
	v_and_b32_e32 v4, 3, v12
	s_ashr_i32 s53, s52, 31
	s_ashr_i32 s61, s60, 31
	v_add_u16_e32 v0, v0, v2
	v_and_or_b32 v4, v1, s14, v4
	s_lshl_b64 s[14:15], s[52:53], 19
	s_lshl_b64 s[16:17], s[60:61], 19
	v_ashrrev_i16_sdwa v0, v213, sext(v0) dst_sel:DWORD dst_unused:UNUSED_PAD src0_sel:DWORD src1_sel:BYTE_0
	s_add_u32 s62, s69, s16
	v_lshlrev_b32_e32 v3, 5, v11
	v_bfe_i32 v13, v0, 0, 16
	v_lshlrev_b32_e32 v0, 1, v1
	v_lshrrev_b32_e32 v2, 2, v1
	s_addc_u32 s63, s70, s17
	s_add_i32 s71, s95, 0
	v_and_b32_e32 v3, 32, v3
	v_and_b32_e32 v0, 24, v0
	v_and_b32_e32 v2, 4, v2
	s_add_i32 m0, s71, 0x10000
	v_or3_b32 v0, v4, v2, v0
	v_add_lshl_u32 v2, v3, v13, 1
	global_load_lds_dwordx4 v172, s[62:63]
	s_add_i32 m0, s71, 0x12000
	v_lshl_add_u32 v164, v0, 11, v2
	s_add_u32 s16, s62, 0x40000
	global_load_lds_dwordx4 v164, s[62:63]
	s_addc_u32 s17, s63, 0
	s_add_i32 m0, s71, 0x14000
	v_writelane_b32 v240, s74, 8
	global_load_lds_dwordx4 v172, s[16:17]
	s_add_i32 m0, s71, 0x16000
	s_add_u32 s64, s20, s14
	s_addc_u32 s65, s68, s15
	s_add_i32 s72, s71, 0x2000
	global_load_lds_dwordx4 v164, s[16:17]
	s_mov_b32 m0, s71
	s_add_u32 s14, s64, 0x40000
	v_lshl_add_u32 v162, v1, 11, v2
	global_load_lds_dwordx4 v160, s[64:65]
	s_mov_b32 m0, s72
	s_addc_u32 s15, s65, 0
	s_add_i32 s73, s71, 0x4000
	v_writelane_b32 v240, s75, 9
	global_load_lds_dwordx4 v162, s[64:65]
	s_mov_b32 m0, s73
	s_add_i32 s74, s71, 0x6000
	global_load_lds_dwordx4 v160, s[14:15]
	s_mov_b32 m0, s74
	v_mov_b32_e32 v165, v173
	global_load_lds_dwordx4 v162, s[14:15]
	v_mov_b32_e32 v161, v173
	v_mov_b32_e32 v163, v173
	v_lshl_add_u64 v[6:7], s[62:63], 0, v[172:173]
	v_lshl_add_u64 v[4:5], s[62:63], 0, v[164:165]
	v_lshl_add_u64 v[2:3], s[64:65], 0, v[160:161]
	s_and_b64 vcc, exec, s[58:59]
	v_lshl_add_u64 v[0:1], s[64:65], 0, v[162:163]
	s_cbranch_vccnz .LBB0_1176
	s_barrier

; #define GAS __attribute__((address_space(1)))
;     __device__ __forceinline__ GAS unsigned char* wsp() const { return (GAS unsigned char*)rd(18); }
; #define PG8_STAGE(bufoff, gbase, voff) do { _Pragma("unroll") for (int _i = 0; _i < 2; ++_i) \
;         __builtin_amdgcn_global_load_lds((const GAS unsigned*)((const GAS char*)(gbase) + (voff)[_i]), (LAS unsigned*)(lds + (bufoff) + ldsw + _i * 8192), 16, 0, 0); } while (0)
; #define PG8_WAIT_V(n) asm volatile("s_waitcnt vmcnt(" #n ")" ::: "memory")
; #define PG8_BAR __builtin_amdgcn_s_barrier()
;     ...
;     for (int i = 0; i < 2; ++i) { int R, C; stage_rc(tid * 16 + i * 8192, R, C); const int Rb = (R & ~31) + perm32(R & 31);
;         voffA[i] = (unsigned)(R * K + C) * 2u; voffB[i] = (unsigned)(Rb * K + C) * 2u; }
;     const size_t kstep = (size_t)(BK * 2);
;     const size_t hstep = (size_t)HALF * K * 2;
;     const size_t tstep = 2 * hstep;
;     const unsigned ldsw = (unsigned)wid * 1024u;
;     const int aoff = lds_byte(wr * 64 + fr, fq * 8), boff = lds_byte(wc * 32 + fr, fq * 8);
;     ...
;     Unit cur, nxt; int ui = 0;
;     if (!S.template next<MODE>(0, cur)) return;
;     Acc acc;
; #pragma unroll
;     for (int a = 0; a < 2; ++a)
; #pragma unroll
;         for (int b = 0; b < 2; ++b)
; #pragma unroll
;             for (int m = 0; m < 4; ++m)
; #pragma unroll
;                 for (int n = 0; n < 2; ++n) acc[a][b][m][n] = (f32x4){0.f, 0.f, 0.f, 0.f};
;     bf16x8 At[4][2], B0[2][2], B1[2][2];
;     const GAS char* cA = (const GAS char*)(g.A + (size_t)cur.seg * g.a_seg) + (size_t)cur.pm * tstep + (MODE ? (size_t)cur.k0 * kstep : 0); const GAS char* cB = (const GAS char*)(g.Bt + (size_t)cur.seg * g.b_seg) + (size_t)cur.pn * tstep + (MODE ? (size_t)cur.k0 * kstep : 0);
;     PG8_STAGE(PG8_SB(0, 0), cB, voffB); PG8_STAGE(PG8_SB(0, 1), cB + hstep, voffB); PG8_STAGE(PG8_SA(0, 0), cA, voffA); PG8_STAGE(PG8_SA(0, 1), cA + hstep, voffA);
;     if (wr == 1) PG8_BAR;
;     PG8_WAIT_V(2); PG8_BAR;
;     PG8_STAGE(PG8_SB(1, 0), cB + kstep, voffB); PG8_STAGE(PG8_SA(1, 0), cA + kstep, voffA); PG8_STAGE(PG8_SB(1, 1), cB + hstep + kstep, voffB);
;     PG8_WAIT_V(6); PG8_BAR;
; __global__ void __launch_bounds__(512, 2) mega_fwd(Params p) {
;     ...
;             { __syncthreads(); pg8::EpiOutSlab E2{F.wsp()}; pg8::gemm_phase<pg8::EpiOutSlab, 1>(F.lds, g, S, E2, F.wave); }
.LBB0_1274:
	v_mov_b32_e32 v0, s18
	s_waitcnt vmcnt(0)
	s_barrier
	ds_read_b64 v[0:1], v0
	v_readlane_b32 s12, v242, 52
	v_readlane_b32 s13, v242, 53
	s_andn2_b64 vcc, exec, s[12:13]
	s_waitcnt lgkmcnt(0)
	v_readfirstlane_b32 s9, v1
	v_readfirstlane_b32 s8, v0
	v_mov_b32_e32 v0, v173
	s_cmp_eq_u32 s100, 2
	s_cbranch_scc0 .Lor_b
	s_mov_b32 s100, 0
	s_branch .LBB0_1282
.Lor_b:
	s_cbranch_vccnz .LBB0_1282
	v_mbcnt_lo_u32_b32 v0, -1, v0
	v_mbcnt_hi_u32_b32 v135, -1, v0
	v_lshl_add_u32 v0, v135, 4, s95
	v_add_u32_e32 v1, 0x2000, v0
	v_ashrrev_i32_e32 v2, 31, v1
	v_lshrrev_b32_e32 v2, 22, v2
	v_add_u32_e32 v2, v1, v2
	v_ashrrev_i32_e32 v2, 10, v2
	v_mul_i32_i24_e32 v3, 0x400, v2
	v_sub_u32_e32 v1, v1, v3
	v_lshrrev_b32_e32 v3, 4, v1
	v_bitop3_b32 v1, v3, v1, 32 bitop3:0x6c
	v_ashrrev_i32_e32 v3, 31, v1
	v_lshrrev_b32_e32 v3, 26, v3
	v_add_u32_e32 v3, v1, v3
	v_ashrrev_i32_e32 v4, 6, v3
	v_and_b32_e32 v3, 0xffc0, v3
	v_sub_u32_e32 v1, v1, v3
	v_lshlrev_b32_e32 v5, 3, v2
	v_lshrrev_b16_e32 v3, 7, v1
	v_and_b32_e32 v5, -16, v5
	v_and_b32_e32 v3, 1, v3
	v_add_u32_e32 v5, v4, v5
	v_add_u16_e32 v1, v1, v3
	v_and_b32_e32 v4, 3, v4
	s_mov_b32 s12, 0x1fffe0
	v_lshrrev_b32_e32 v6, 2, v5
	v_lshlrev_b32_e32 v7, 1, v5
	v_lshlrev_b32_e32 v2, 5, v2
	v_ashrrev_i16_sdwa v1, v213, sext(v1) dst_sel:DWORD dst_unused:UNUSED_PAD src0_sel:DWORD src1_sel:BYTE_0
	v_and_or_b32 v4, v5, s12, v4
	v_and_b32_e32 v6, 4, v6
	v_and_b32_e32 v7, 24, v7
	v_and_b32_e32 v2, 32, v2
	v_bfe_i32 v1, v1, 0, 16
	v_or3_b32 v4, v4, v6, v7
	v_add_lshl_u32 v1, v2, v1, 1
	v_lshl_add_u32 v128, v4, 11, v1
	v_lshl_add_u32 v130, v5, 11, v1
	v_ashrrev_i32_e32 v1, 31, v0
	v_lshrrev_b32_e32 v1, 22, v1
	v_add_u32_e32 v1, v0, v1
	v_ashrrev_i32_e32 v1, 10, v1
	v_mul_i32_i24_e32 v2, 0x400, v1
	v_sub_u32_e32 v0, v0, v2
	v_lshrrev_b32_e32 v2, 4, v0
	v_bitop3_b32 v0, v2, v0, 32 bitop3:0x6c
	v_ashrrev_i32_e32 v2, 31, v0
	v_lshrrev_b32_e32 v2, 26, v2
	v_add_u32_e32 v2, v0, v2
	v_lshlrev_b32_e32 v4, 3, v1
	v_ashrrev_i32_e32 v3, 6, v2
	v_and_b32_e32 v4, -16, v4
	v_add_u32_e32 v4, v3, v4
	v_and_b32_e32 v3, 3, v3
	v_and_or_b32 v3, v4, s12, v3
	v_readlane_b32 s12, v241, 15
	v_readlane_b32 s13, v241, 16
	s_add_u32 s16, s20, s12
	v_and_b32_e32 v2, 0xc0, v2
	s_addc_u32 s17, s68, s13
	v_readlane_b32 s12, v241, 17
	v_sub_u32_e32 v0, v0, v2
	v_readlane_b32 s13, v241, 18
	s_add_u32 s12, s69, s12
	v_lshrrev_b32_e32 v5, 2, v4
	v_lshlrev_b32_e32 v6, 1, v4
	v_lshlrev_b32_e32 v1, 5, v1
	v_ashrrev_i16_sdwa v0, v213, sext(v0) dst_sel:DWORD dst_unused:UNUSED_PAD src0_sel:DWORD src1_sel:BYTE_0
	s_addc_u32 s13, s70, s13
	v_readlane_b32 s24, v242, 54
	v_and_b32_e32 v5, 4, v5
	v_and_b32_e32 v6, 24, v6
	v_and_b32_e32 v1, 32, v1
	v_bfe_i32 v0, v0, 0, 16
	v_readlane_b32 s25, v242, 55
	s_add_u32 s12, s12, s24
	v_or3_b32 v3, v3, v5, v6
	v_add_lshl_u32 v0, v1, v0, 1
	s_addc_u32 s13, s13, s25
	s_add_i32 s52, s95, 0
	v_lshl_add_u32 v172, v3, 11, v0
	s_add_i32 m0, s52, 0x10000
	v_lshl_add_u32 v132, v4, 11, v0
	global_load_lds_dwordx4 v172, s[12:13]
	s_add_i32 m0, s52, 0x12000
	s_add_u32 s14, s12, 0x40000
	global_load_lds_dwordx4 v128, s[12:13]
	s_addc_u32 s15, s13, 0
	s_add_i32 m0, s52, 0x14000
	s_nop 0
	global_load_lds_dwordx4 v172, s[14:15]
	s_add_i32 m0, s52, 0x16000
	s_nop 0
	global_load_lds_dwordx4 v128, s[14:15]
	s_add_u32 s14, s16, s24
	s_addc_u32 s15, s17, s25
	s_add_i32 s53, s52, 0x2000
	s_mov_b32 m0, s52
	s_add_u32 s16, s14, 0x40000
	global_load_lds_dwordx4 v132, s[14:15]
	s_mov_b32 m0, s53
	s_addc_u32 s17, s15, 0
	s_add_i32 s60, s52, 0x4000
	global_load_lds_dwordx4 v130, s[14:15]
	s_mov_b32 m0, s60
	s_add_i32 s61, s52, 0x6000
	global_load_lds_dwordx4 v132, s[16:17]
	s_mov_b32 m0, s61
	s_and_b64 vcc, exec, s[58:59]
	global_load_lds_dwordx4 v130, s[16:17]
	s_cbranch_vccnz .LBB0_1277
	s_barrier

; #define GAS __attribute__((address_space(1)))
; __device__ __forceinline__ int lane_id() { unsigned z = 0u; asm volatile("" : "+v"(z)); return (int)__builtin_amdgcn_mbcnt_hi(~0u, __builtin_amdgcn_mbcnt_lo(~0u, z)); }
; __device__ __forceinline__ v4u pack8(const f32x4 a, const f32x4 b) { v4u w; w.x = cvt_pk_bf16(a[0], a[1]); w.y = cvt_pk_bf16(a[2], a[3]); w.z = cvt_pk_bf16(b[0], b[1]); w.w = cvt_pk_bf16(b[2], b[3]); return w; }
; __device__ __forceinline__ void xcd_barrier(const XcdBarrier& b, int wave) {
;     asm volatile("s_waitcnt vmcnt(0)" ::: "memory");
;     __syncthreads();
;     if (wave == 0 && lane_id() == 0) {
;         GAS unsigned* bar = b.bar;
;         __builtin_amdgcn_s_waitcnt(0);
;         unsigned nloc = b.st[0], nx = b.st[1];
;         if (nloc == 0u) { xcd_barrier_complete(bar, b.x, nloc, nx); b.st[0] = nloc; b.st[1] = nx; }
;     __device__ __forceinline__ void operator()(Acc& acc, const Unit& u, int wr, int wc, int fr, int fq, LAS unsigned char* lds) const {
;         {
;             GAS bf16* sl = (GAS bf16*)(ws + WS_SLAB_O) + (size_t)u.slab * 65536 + (size_t)(wr * 64 + fr) * 256 + wc * 32 + 8 * fq;
; #pragma unroll
;             for (int ai = 0; ai < 2; ++ai)
; #pragma unroll
;                 for (int m = 0; m < 4; ++m)
; #pragma unroll
;                     for (int bj = 0; bj < 2; ++bj) *(GAS v4u*)(sl + (size_t)(ai * 128 + m * 16) * 256 + bj * 128) = pack8(acc[ai][bj][m][0], acc[ai][bj][m][1]);
.LBB0_1281:
	v_ashrrev_i32_e32 v128, 1, v135
	v_mov_b32_e32 v135, v173
	v_lshlrev_b64 v[130:131], 9, v[134:135]
	v_lshl_add_u64 v[130:131], s[8:9], 0, v[130:131]
	v_readlane_b32 s8, v241, 7
	v_and_b32_e32 v128, -8, v128
	s_lshl_b32 s20, s8, 1
	v_ashrrev_i32_e32 v129, 31, v128
	v_lshl_add_u64 v[130:131], v[130:131], 0, s[20:21]
	v_readlane_b32 s8, v242, 35
	v_lshl_add_u64 v[128:129], v[128:129], 1, v[130:131]
	v_readlane_b32 s9, v242, 36
	v_cvt_pk_bf16_f32 v124, v124, v125
	v_cvt_pk_bf16_f32 v125, v126, v127
	v_lshl_add_u64 v[128:129], v[128:129], 0, s[8:9]
	s_mov_b64 s[8:9], 0xfd80000
	v_lshl_add_u64 v[130:131], v[128:129], 0, s[8:9]
	s_mov_b32 s8, 0xfd80000
	v_cvt_pk_bf16_f32 v126, v120, v121
	v_add_co_u32_e32 v120, vcc, s8, v128
	v_cvt_pk_bf16_f32 v108, v108, v109
	s_nop 0
	v_addc_co_u32_e32 v121, vcc, 0, v129, vcc
	v_cvt_pk_bf16_f32 v109, v110, v111
	v_cvt_pk_bf16_f32 v110, v104, v105
	v_cvt_pk_bf16_f32 v111, v106, v107
	s_mov_b32 s8, 0xfd82000
	global_store_dwordx4 v[130:131], v[108:111], off offset:256
	v_cvt_pk_bf16_f32 v92, v92, v93
	v_cvt_pk_bf16_f32 v93, v94, v95
	v_add_co_u32_e32 v108, vcc, s8, v128
	v_cvt_pk_bf16_f32 v94, v88, v89
	s_nop 0
	v_addc_co_u32_e32 v109, vcc, 0, v129, vcc
	v_cvt_pk_bf16_f32 v95, v90, v91
	s_mov_b32 s8, 0xfd84000
	global_store_dwordx4 v[108:109], v[92:95], off offset:256
	v_cvt_pk_bf16_f32 v76, v76, v77
	v_cvt_pk_bf16_f32 v77, v78, v79
	v_add_co_u32_e32 v92, vcc, s8, v128
	v_cvt_pk_bf16_f32 v78, v72, v73
	s_nop 0
	v_addc_co_u32_e32 v93, vcc, 0, v129, vcc
	v_cvt_pk_bf16_f32 v79, v74, v75
	s_mov_b32 s8, 0xfd86000
	global_store_dwordx4 v[92:93], v[76:79], off offset:256
	v_cvt_pk_bf16_f32 v60, v60, v61
	v_cvt_pk_bf16_f32 v61, v62, v63
	v_add_co_u32_e32 v76, vcc, s8, v128
	s_mov_b32 s8, 0xfd90000
	s_nop 0
	v_addc_co_u32_e32 v77, vcc, 0, v129, vcc
	v_cvt_pk_bf16_f32 v62, v56, v57
	v_add_co_u32_e32 v56, vcc, s8, v128
	v_cvt_pk_bf16_f32 v44, v44, v45
	s_nop 0
	v_addc_co_u32_e32 v57, vcc, 0, v129, vcc
	v_cvt_pk_bf16_f32 v45, v46, v47
	v_cvt_pk_bf16_f32 v46, v40, v41
	v_cvt_pk_bf16_f32 v47, v42, v43
	s_mov_b32 s8, 0xfd92000
	global_store_dwordx4 v[56:57], v[44:47], off offset:256
	v_cvt_pk_bf16_f32 v28, v28, v29
	v_cvt_pk_bf16_f32 v29, v30, v31
	v_add_co_u32_e32 v44, vcc, s8, v128
	v_cvt_pk_bf16_f32 v30, v24, v25
	s_nop 0
	v_addc_co_u32_e32 v45, vcc, 0, v129, vcc
	v_cvt_pk_bf16_f32 v31, v26, v27
	s_mov_b32 s8, 0xfd94000
	global_store_dwordx4 v[44:45], v[28:31], off offset:256
	v_cvt_pk_bf16_f32 v12, v12, v13
	v_cvt_pk_bf16_f32 v13, v14, v15
	v_add_co_u32_e32 v28, vcc, s8, v128
	v_cvt_pk_bf16_f32 v14, v8, v9
	s_nop 0
	v_addc_co_u32_e32 v29, vcc, 0, v129, vcc
	v_cvt_pk_bf16_f32 v15, v10, v11
	s_mov_b32 s8, 0xfd96000
	global_store_dwordx4 v[28:29], v[12:15], off offset:256
	v_cvt_pk_bf16_f32 v127, v122, v123
	v_cvt_pk_bf16_f32 v104, v116, v117
	v_add_co_u32_e32 v12, vcc, s8, v128
	v_cvt_pk_bf16_f32 v105, v118, v119
	v_cvt_pk_bf16_f32 v106, v112, v113
	v_cvt_pk_bf16_f32 v107, v114, v115
	v_cvt_pk_bf16_f32 v88, v100, v101
	v_cvt_pk_bf16_f32 v89, v102, v103
	v_cvt_pk_bf16_f32 v90, v96, v97
	v_cvt_pk_bf16_f32 v91, v98, v99
	v_cvt_pk_bf16_f32 v72, v84, v85
	v_cvt_pk_bf16_f32 v73, v86, v87
	v_cvt_pk_bf16_f32 v74, v80, v81
	v_cvt_pk_bf16_f32 v75, v82, v83
	v_cvt_pk_bf16_f32 v68, v68, v69
	v_cvt_pk_bf16_f32 v69, v70, v71
	v_cvt_pk_bf16_f32 v70, v64, v65
	v_cvt_pk_bf16_f32 v71, v66, v67
	v_cvt_pk_bf16_f32 v63, v58, v59
	v_cvt_pk_bf16_f32 v40, v52, v53
	v_cvt_pk_bf16_f32 v41, v54, v55
	v_cvt_pk_bf16_f32 v42, v48, v49
	v_cvt_pk_bf16_f32 v43, v50, v51
	v_cvt_pk_bf16_f32 v24, v36, v37
	v_cvt_pk_bf16_f32 v25, v38, v39
	v_cvt_pk_bf16_f32 v26, v32, v33
	v_cvt_pk_bf16_f32 v27, v34, v35
	v_cvt_pk_bf16_f32 v8, v20, v21
	v_cvt_pk_bf16_f32 v9, v22, v23
	v_cvt_pk_bf16_f32 v10, v16, v17
	v_cvt_pk_bf16_f32 v11, v18, v19
	v_addc_co_u32_e32 v13, vcc, 0, v129, vcc
	v_cvt_pk_bf16_f32 v4, v4, v5
	v_cvt_pk_bf16_f32 v5, v6, v7
	v_cvt_pk_bf16_f32 v6, v0, v1
	v_cvt_pk_bf16_f32 v7, v2, v3
	global_store_dwordx4 v[120:121], v[124:127], off
	global_store_dwordx4 v[108:109], v[104:107], off
	global_store_dwordx4 v[92:93], v[88:91], off
	global_store_dwordx4 v[76:77], v[72:75], off
	global_store_dwordx4 v[76:77], v[68:71], off offset:256
	global_store_dwordx4 v[56:57], v[60:63], off
	global_store_dwordx4 v[44:45], v[40:43], off
	global_store_dwordx4 v[28:29], v[24:27], off
	global_store_dwordx4 v[12:13], v[8:11], off
	global_store_dwordx4 v[12:13], v[4:7], off offset:256
	s_waitcnt vmcnt(0)
	s_barrier
.LBB0_1282:
	s_cmp_eq_u32 s100, 1
	s_cbranch_scc0 .Lor_end
	s_mov_b32 s100, 2
	s_branch .Lor_pre
.Lor_end:
	s_waitcnt vmcnt(0)
	s_and_b64 vcc, exec, s[54:55]
	s_waitcnt vmcnt(0)
	s_barrier
	s_cbranch_vccnz .LBB0_1327
	v_mov_b32_e32 v0, v173
	s_nop 0
	v_mbcnt_lo_u32_b32 v0, -1, v0
	v_mbcnt_hi_u32_b32 v0, -1, v0
	v_cmp_eq_u32_e32 vcc, 0, v0
	s_and_saveexec_b64 s[8:9], vcc
	s_cbranch_execz .LBB0_1326
	v_readlane_b32 s12, v243, 2
	s_waitcnt vmcnt(0) expcnt(0) lgkmcnt(0)
	s_nop 0
	v_mov_b32_e32 v0, s12
	ds_read_b32 v2, v0
	ds_read_b32 v1, v0 offset:4
	s_waitcnt lgkmcnt(1)
	v_cmp_ne_u32_e32 vcc, 0, v2
	s_cbranch_vccnz .LBB0_1297
	v_readlane_b32 s14, v243, 0
	v_readlane_b32 s15, v243, 1
	s_load_dwordx2 s[12:13], s[14:15], 0x4
	s_mov_b32 s24, 1
	s_waitcnt lgkmcnt(0)
	s_mul_i32 s20, s12, s2
	s_mul_i32 s20, s20, s13
	s_branch .LBB0_1287
